# MLA loop: max tree split per accumulator so the first half runs inside the MFMA result wait (pad 11->4 states, 16 ops), K fragment reads issued ahead of the global loads
# speedup vs baseline: 1.0197x; 1.0197x over previous
.Lmla_loop:
	ds_read_b128 v[48:51], v169 offset:13312
	ds_read_b128 v[52:55], v169 offset:13344
	ds_read_b128 v[116:119], v169 offset:19968
	ds_read_b128 v[120:123], v169 offset:20000
	global_load_dwordx4 v[104:107], v154, s[98:99]
	s_mov_b64 exec, s[8:9]
	global_load_dwordx4 v[108:111], v156, s[98:99]
	s_mov_b64 exec, -1
	global_load_dwordx4 v[112:115], v158, s[100:101]
	s_add_u32 s98, s98, 0x18000
	s_addc_u32 s99, s99, 0
	s_add_u32 s100, s100, 0x80
	s_addc_u32 s101, s101, 0
	s_waitcnt lgkmcnt(3)
	v_mfma_f32_32x32x16_bf16 v[64:79], v[48:51], v[100:103], v[32:47]
	ds_read_b128 v[124:127], v169 offset:13376
	ds_read_b128 v[128:131], v169 offset:13408
	ds_read_b128 v[132:135], v169 offset:20032
	ds_read_b128 v[136:139], v169 offset:20064
	s_waitcnt lgkmcnt(4)
	v_mfma_f32_32x32x16_bf16 v[64:79], v[52:55], v[96:99], v[64:79]
	v_mfma_f32_32x32x16_bf16 v[48:63], v[116:119], v[100:103], v[32:47]
	v_mfma_f32_32x32x16_bf16 v[48:63], v[120:123], v[96:99], v[48:63]
	s_waitcnt lgkmcnt(1)
	v_mfma_f32_32x32x16_bf16 v[64:79], v[124:127], v[92:95], v[64:79]
	v_mfma_f32_32x32x16_bf16 v[48:63], v[132:135], v[92:95], v[48:63]
	v_mfma_f32_32x32x16_bf16 v[64:79], v[128:131], v[88:91], v[64:79]
	ds_read_b128 v[116:119], v169 offset:13440
	ds_read_b128 v[120:123], v169 offset:13472
	ds_read_b128 v[128:131], v169 offset:20096
	ds_read_b128 v[176:179], v169 offset:20128
	s_waitcnt lgkmcnt(3)
	v_mfma_f32_32x32x16_bf16 v[48:63], v[136:139], v[88:91], v[48:63]
	v_mfma_f32_32x32x16_bf16 v[64:79], v[116:119], v[84:87], v[64:79]
	ds_read_b128 v[136:139], v170 offset:35840
	ds_read_b128 v[124:127], v170 offset:35872
	s_waitcnt lgkmcnt(3)
	v_mfma_f32_32x32x16_bf16 v[48:63], v[128:131], v[84:87], v[48:63]
	v_mfma_f32_32x32x16_bf16 v[64:79], v[120:123], v[80:83], v[64:79]
	ds_read_b128 v[132:135], v170 offset:35904
	ds_read_b128 v[120:123], v170 offset:35936
	ds_read_b128 v[144:147], v170 offset:40448
	ds_read_b128 v[140:143], v170 offset:40480
	ds_read_b128 v[128:131], v170 offset:40512
	ds_read_b128 v[116:119], v170 offset:40544
	s_waitcnt lgkmcnt(8)
	v_mfma_f32_32x32x16_bf16 v[48:63], v[176:179], v[80:83], v[48:63]
	s_add_i32 s43, s43, 1
	s_nop 3
	v_max3_f32 v148, v64, v65, v66
	v_max3_f32 v160, v67, v68, v69
	v_max3_f32 v148, v148, v70, v71
	v_max3_f32 v160, v160, v72, v73
	v_max3_f32 v148, v148, v74, v75
	v_max3_f32 v160, v160, v76, v77
	v_max3_f32 v148, v148, v78, v79
	v_max3_f32 v161, v48, v49, v50
	v_max3_f32 v176, v51, v52, v53
	v_max3_f32 v161, v161, v54, v55
	v_max3_f32 v176, v176, v56, v57
	v_max3_f32 v161, v161, v58, v59
	v_max3_f32 v176, v176, v60, v61
	v_max3_f32 v161, v161, v62, v63
	v_max3_f32 v148, v148, v160, v161
	v_max_f32_e32 v148, v148, v176
	v_cmp_lt_f32_e32 vcc, s59, v148
	s_cbranch_vccz .Lmla_norescale_1
	v_mov_b32_e32 v160, v148
	s_nop 1
	v_permlane32_swap_b32_e32 v148, v160
	v_max_f32_e32 v148, v148, v160
	v_max_f32_e32 v32, v148, v148
	v_max_f32_e32 v148, 0, v32
	v_exp_f32_e64 v160, -v148
	v_add_f32_e32 v168, v168, v148
	v_xor_b32_e32 v32, 0x80000000, v168
	v_mov_b32_e32 v33, v32
	v_mov_b32_e32 v34, v32
	v_mov_b32_e32 v35, v32
	v_mov_b32_e32 v36, v32
	v_mov_b32_e32 v37, v32
	v_mov_b32_e32 v38, v32
	v_mov_b32_e32 v39, v32
	v_mov_b32_e32 v40, v32
	v_mov_b32_e32 v41, v32
	v_mov_b32_e32 v42, v32
	v_mov_b32_e32 v43, v32
	v_mov_b32_e32 v44, v32
	v_mov_b32_e32 v45, v32
	v_mov_b32_e32 v46, v32
	v_mov_b32_e32 v47, v32
	v_pk_add_f32 v[64:65], v[64:65], v[148:149] op_sel_hi:[1,0] neg_lo:[0,1] neg_hi:[0,1]
	v_pk_add_f32 v[48:49], v[48:49], v[148:149] op_sel_hi:[1,0] neg_lo:[0,1] neg_hi:[0,1]
	v_pk_add_f32 v[66:67], v[66:67], v[148:149] op_sel_hi:[1,0] neg_lo:[0,1] neg_hi:[0,1]
	v_pk_add_f32 v[50:51], v[50:51], v[148:149] op_sel_hi:[1,0] neg_lo:[0,1] neg_hi:[0,1]
	v_pk_add_f32 v[68:69], v[68:69], v[148:149] op_sel_hi:[1,0] neg_lo:[0,1] neg_hi:[0,1]
	v_pk_add_f32 v[52:53], v[52:53], v[148:149] op_sel_hi:[1,0] neg_lo:[0,1] neg_hi:[0,1]
	v_pk_add_f32 v[70:71], v[70:71], v[148:149] op_sel_hi:[1,0] neg_lo:[0,1] neg_hi:[0,1]
	v_pk_add_f32 v[54:55], v[54:55], v[148:149] op_sel_hi:[1,0] neg_lo:[0,1] neg_hi:[0,1]
	v_pk_add_f32 v[72:73], v[72:73], v[148:149] op_sel_hi:[1,0] neg_lo:[0,1] neg_hi:[0,1]
	v_pk_add_f32 v[56:57], v[56:57], v[148:149] op_sel_hi:[1,0] neg_lo:[0,1] neg_hi:[0,1]
	v_pk_add_f32 v[74:75], v[74:75], v[148:149] op_sel_hi:[1,0] neg_lo:[0,1] neg_hi:[0,1]
	v_pk_add_f32 v[58:59], v[58:59], v[148:149] op_sel_hi:[1,0] neg_lo:[0,1] neg_hi:[0,1]
	v_pk_add_f32 v[76:77], v[76:77], v[148:149] op_sel_hi:[1,0] neg_lo:[0,1] neg_hi:[0,1]
	v_pk_add_f32 v[60:61], v[60:61], v[148:149] op_sel_hi:[1,0] neg_lo:[0,1] neg_hi:[0,1]
	v_pk_add_f32 v[78:79], v[78:79], v[148:149] op_sel_hi:[1,0] neg_lo:[0,1] neg_hi:[0,1]
	v_pk_add_f32 v[62:63], v[62:63], v[148:149] op_sel_hi:[1,0] neg_lo:[0,1] neg_hi:[0,1]
	v_pk_mul_f32 v[30:31], v[30:31], v[160:161] op_sel_hi:[1,0]
	v_pk_mul_f32 v[28:29], v[28:29], v[160:161] op_sel_hi:[1,0]
	v_pk_mul_f32 v[26:27], v[26:27], v[160:161] op_sel_hi:[1,0]
	v_pk_mul_f32 v[24:25], v[24:25], v[160:161] op_sel_hi:[1,0]
	v_pk_mul_f32 v[22:23], v[22:23], v[160:161] op_sel_hi:[1,0]
	v_pk_mul_f32 v[20:21], v[20:21], v[160:161] op_sel_hi:[1,0]
	v_pk_mul_f32 v[18:19], v[18:19], v[160:161] op_sel_hi:[1,0]
	v_pk_mul_f32 v[16:17], v[16:17], v[160:161] op_sel_hi:[1,0]
	v_pk_mul_f32 v[14:15], v[14:15], v[160:161] op_sel_hi:[1,0]
	v_pk_mul_f32 v[12:13], v[12:13], v[160:161] op_sel_hi:[1,0]
	v_pk_mul_f32 v[10:11], v[10:11], v[160:161] op_sel_hi:[1,0]
	v_pk_mul_f32 v[8:9], v[8:9], v[160:161] op_sel_hi:[1,0]
	v_pk_mul_f32 v[6:7], v[6:7], v[160:161] op_sel_hi:[1,0]
	v_pk_mul_f32 v[4:5], v[4:5], v[160:161] op_sel_hi:[1,0]
	v_pk_mul_f32 v[2:3], v[2:3], v[160:161] op_sel_hi:[1,0]
	v_pk_mul_f32 v[0:1], v[0:1], v[160:161] op_sel_hi:[1,0]
	v_pk_mul_f32 v[152:153], v[152:153], v[160:161] op_sel_hi:[1,0]
	v_pk_mul_f32 v[150:151], v[150:151], v[160:161] op_sel_hi:[1,0]
; #define AT_QK_LD0(kb_) do { if constexpr (NEGM) { const LAS unsigned char* kbp_ = Kl + (kb_) * KBUF + r32 * KROWB + hi * 16; AT_KLD2(0); __builtin_amdgcn_sched_barrier(0); } } while (0)
; template <int DQK, int DV, int RH, bool NEGM> ...
;     ...
;     const int NT = nkv / 64;
;     AT_GLOAD(0); AT_LSTORE(0, 0); __syncthreads();
;     int vs_prev = 2, vs_cur = 0, vs_next = 1;
;     if (!grpB) {
;         for (int t = 0; t < NT; ++t) {
;             const int kb = t & 1;
;             if (t + 1 < NT) AT_GLOAD(t + 1);
;             f32x16 p[RH][2];
;             AT_QK_LD0(kb); AT_QK(kb); AT_VLOAD(vs_cur); AT_SOFTMAX(); AT_PV(vs_cur);
;             if (t + 1 < NT) AT_LSTORE(kb ^ 1, vs_next);
;             __syncthreads();
.Lmla_norescale_1:
	v_exp_f32_e32 v160, v64
	v_exp_f32_e32 v161, v65
	v_exp_f32_e32 v64, v66
	v_exp_f32_e32 v65, v67
	v_exp_f32_e32 v68, v68
	v_exp_f32_e32 v69, v69
	v_exp_f32_e32 v66, v70
	v_exp_f32_e32 v67, v71
	v_cvt_pk_bf16_f32 v176, v160, v161
	v_cvt_pk_bf16_f32 v177, v64, v65
	v_cvt_pk_bf16_f32 v178, v68, v69
	v_cvt_pk_bf16_f32 v179, v66, v67
	v_exp_f32_e32 v70, v74
	v_exp_f32_e32 v71, v75
	s_waitcnt lgkmcnt(0)
	v_mfma_f32_32x32x16_bf16 v[16:31], v[136:139], v[176:179], v[16:31]
	v_exp_f32_e32 v136, v72
	v_exp_f32_e32 v137, v73
	v_exp_f32_e32 v74, v76
	v_exp_f32_e32 v75, v77
	v_exp_f32_e32 v72, v78
	v_exp_f32_e32 v73, v79
	v_exp_f32_e32 v76, v48
	v_mfma_f32_32x32x16_bf16 v[0:15], v[144:147], v[176:179], v[0:15]
	v_cvt_pk_bf16_f32 v144, v136, v137
	v_cvt_pk_bf16_f32 v145, v70, v71
	v_cvt_pk_bf16_f32 v146, v74, v75
	v_cvt_pk_bf16_f32 v147, v72, v73
	v_exp_f32_e32 v77, v49
	v_exp_f32_e32 v48, v50
	v_exp_f32_e32 v49, v51
	v_mfma_f32_32x32x16_bf16 v[16:31], v[124:127], v[144:147], v[16:31]
	v_exp_f32_e32 v52, v52
	v_exp_f32_e32 v53, v53
	v_exp_f32_e32 v50, v54
	v_exp_f32_e32 v51, v55
	v_cvt_pk_bf16_f32 v124, v76, v77
	v_cvt_pk_bf16_f32 v125, v48, v49
	v_cvt_pk_bf16_f32 v126, v52, v53
	v_mfma_f32_32x32x16_bf16 v[0:15], v[140:143], v[144:147], v[0:15]
	v_cvt_pk_bf16_f32 v127, v50, v51
	v_exp_f32_e32 v78, v56
	v_exp_f32_e32 v79, v57
	v_exp_f32_e32 v54, v58
	v_exp_f32_e32 v55, v59
	v_exp_f32_e32 v58, v60
	v_exp_f32_e32 v59, v61
	v_mfma_f32_32x32x16_bf16 v[16:31], v[132:135], v[124:127], v[16:31]
	v_exp_f32_e32 v56, v62
	v_exp_f32_e32 v57, v63
	v_cvt_pk_bf16_f32 v60, v78, v79
	v_cvt_pk_bf16_f32 v61, v54, v55
	v_cvt_pk_bf16_f32 v62, v58, v59
	v_cvt_pk_bf16_f32 v63, v56, v57
	v_mfma_f32_32x32x16_bf16 v[0:15], v[128:131], v[124:127], v[0:15]
	v_mfma_f32_32x32x16_bf16 v[16:31], v[120:123], v[60:63], v[16:31]
	v_mfma_f32_32x32x16_bf16 v[0:15], v[116:119], v[60:63], v[0:15]
	s_waitcnt vmcnt(1)
	ds_write_b128 v244, v[104:107]
	s_mov_b64 exec, s[8:9]
	ds_write_b128 v245, v[108:111]
	s_mov_b64 exec, -1
	s_waitcnt vmcnt(0)
	ds_write2_b64 v247, v[112:113], v[114:115] offset1:2
	v_pk_add_f32 v[48:49], v[64:65], v[48:49]
	v_pk_add_f32 v[60:61], v[160:161], v[76:77]
	v_pk_add_f32 v[48:49], v[152:153], v[48:49]
	v_pk_add_f32 v[50:51], v[66:67], v[50:51]
	v_pk_add_f32 v[60:61], v[150:151], v[60:61]
	v_pk_add_f32 v[52:53], v[68:69], v[52:53]
	v_pk_add_f32 v[48:49], v[50:51], v[48:49]
	v_pk_add_f32 v[50:51], v[70:71], v[54:55]
	v_pk_add_f32 v[52:53], v[52:53], v[60:61]
	v_pk_add_f32 v[60:61], v[136:137], v[78:79]
	v_pk_add_f32 v[48:49], v[50:51], v[48:49]
	v_pk_add_f32 v[50:51], v[72:73], v[56:57]
	v_pk_add_f32 v[52:53], v[60:61], v[52:53]
	v_pk_add_f32 v[58:59], v[74:75], v[58:59]
	v_pk_add_f32 v[152:153], v[50:51], v[48:49]
	v_pk_add_f32 v[150:151], v[58:59], v[52:53]
	s_waitcnt lgkmcnt(0)
	s_barrier
	ds_read_b128 v[48:51], v169
	ds_read_b128 v[52:55], v169 offset:32
	ds_read_b128 v[116:119], v169 offset:6656
	ds_read_b128 v[120:123], v169 offset:6688
	global_load_dwordx4 v[104:107], v154, s[98:99]
	s_mov_b64 exec, s[8:9]
	global_load_dwordx4 v[108:111], v156, s[98:99]
	s_mov_b64 exec, -1
	global_load_dwordx4 v[112:115], v158, s[100:101]
	s_add_u32 s98, s98, 0x18000
	s_addc_u32 s99, s99, 0
	s_add_u32 s100, s100, 0x80
	s_addc_u32 s101, s101, 0
	s_waitcnt lgkmcnt(3)
	v_mfma_f32_32x32x16_bf16 v[64:79], v[48:51], v[100:103], v[32:47]
	ds_read_b128 v[124:127], v169 offset:64
	ds_read_b128 v[128:131], v169 offset:96
	ds_read_b128 v[132:135], v169 offset:6720
	ds_read_b128 v[136:139], v169 offset:6752
	s_waitcnt lgkmcnt(4)
	v_mfma_f32_32x32x16_bf16 v[64:79], v[52:55], v[96:99], v[64:79]
	v_mfma_f32_32x32x16_bf16 v[48:63], v[116:119], v[100:103], v[32:47]
	v_mfma_f32_32x32x16_bf16 v[48:63], v[120:123], v[96:99], v[48:63]
	s_waitcnt lgkmcnt(1)
	v_mfma_f32_32x32x16_bf16 v[64:79], v[124:127], v[92:95], v[64:79]
	v_mfma_f32_32x32x16_bf16 v[48:63], v[132:135], v[92:95], v[48:63]
	v_mfma_f32_32x32x16_bf16 v[64:79], v[128:131], v[88:91], v[64:79]
	ds_read_b128 v[116:119], v169 offset:128
	ds_read_b128 v[120:123], v169 offset:160
	ds_read_b128 v[128:131], v169 offset:6784
	ds_read_b128 v[176:179], v169 offset:6816
	s_waitcnt lgkmcnt(3)
	v_mfma_f32_32x32x16_bf16 v[48:63], v[136:139], v[88:91], v[48:63]
	v_mfma_f32_32x32x16_bf16 v[64:79], v[116:119], v[84:87], v[64:79]
	ds_read_b128 v[136:139], v170 offset:45056
	ds_read_b128 v[124:127], v170 offset:45088
	s_waitcnt lgkmcnt(3)
	v_mfma_f32_32x32x16_bf16 v[48:63], v[128:131], v[84:87], v[48:63]
	v_mfma_f32_32x32x16_bf16 v[64:79], v[120:123], v[80:83], v[64:79]
	ds_read_b128 v[132:135], v170 offset:45120
	ds_read_b128 v[120:123], v170 offset:45152
	ds_read_b128 v[144:147], v170 offset:49664
	ds_read_b128 v[140:143], v170 offset:49696
	ds_read_b128 v[128:131], v170 offset:49728
	ds_read_b128 v[116:119], v170 offset:49760
	s_waitcnt lgkmcnt(8)
	v_mfma_f32_32x32x16_bf16 v[48:63], v[176:179], v[80:83], v[48:63]
	s_add_i32 s43, s43, 1
	s_nop 3
	v_max3_f32 v148, v64, v65, v66
	v_max3_f32 v160, v67, v68, v69
	v_max3_f32 v148, v148, v70, v71
	v_max3_f32 v160, v160, v72, v73
	v_max3_f32 v148, v148, v74, v75
	v_max3_f32 v160, v160, v76, v77
	v_max3_f32 v148, v148, v78, v79
	v_max3_f32 v161, v48, v49, v50
	v_max3_f32 v176, v51, v52, v53
	v_max3_f32 v161, v161, v54, v55
	v_max3_f32 v176, v176, v56, v57
	v_max3_f32 v161, v161, v58, v59
	v_max3_f32 v176, v176, v60, v61
	v_max3_f32 v161, v161, v62, v63
	v_max3_f32 v148, v148, v160, v161
	v_max_f32_e32 v148, v148, v176
	v_cmp_lt_f32_e32 vcc, s59, v148
	s_cbranch_vccz .Lmla_norescale_2
; #define AT_QK_LD0(kb_) do { if constexpr (NEGM) { const LAS unsigned char* kbp_ = Kl + (kb_) * KBUF + r32 * KROWB + hi * 16; AT_KLD2(0); __builtin_amdgcn_sched_barrier(0); } } while (0)
; template <int DQK, int DV, int RH, bool NEGM> ...
;     ...
;     const int NT = nkv / 64;
;     AT_GLOAD(0); AT_LSTORE(0, 0); __syncthreads();
;     int vs_prev = 2, vs_cur = 0, vs_next = 1;
;     if (!grpB) {
;         for (int t = 0; t < NT; ++t) {
;             const int kb = t & 1;
;             if (t + 1 < NT) AT_GLOAD(t + 1);
;             f32x16 p[RH][2];
;             AT_QK_LD0(kb); AT_QK(kb); AT_VLOAD(vs_cur); AT_SOFTMAX(); AT_PV(vs_cur);
;             if (t + 1 < NT) AT_LSTORE(kb ^ 1, vs_next);
;             __syncthreads();
	v_mov_b32_e32 v160, v148
	s_nop 1
	v_permlane32_swap_b32_e32 v148, v160
	v_max_f32_e32 v148, v148, v160
	v_max_f32_e32 v32, v148, v148
	v_max_f32_e32 v148, 0, v32
	v_exp_f32_e64 v160, -v148
	v_add_f32_e32 v168, v168, v148
	v_xor_b32_e32 v32, 0x80000000, v168
	v_mov_b32_e32 v33, v32
	v_mov_b32_e32 v34, v32
	v_mov_b32_e32 v35, v32
	v_mov_b32_e32 v36, v32
	v_mov_b32_e32 v37, v32
	v_mov_b32_e32 v38, v32
	v_mov_b32_e32 v39, v32
	v_mov_b32_e32 v40, v32
	v_mov_b32_e32 v41, v32
	v_mov_b32_e32 v42, v32
	v_mov_b32_e32 v43, v32
	v_mov_b32_e32 v44, v32
	v_mov_b32_e32 v45, v32
	v_mov_b32_e32 v46, v32
	v_mov_b32_e32 v47, v32
	v_pk_add_f32 v[64:65], v[64:65], v[148:149] op_sel_hi:[1,0] neg_lo:[0,1] neg_hi:[0,1]
	v_pk_add_f32 v[48:49], v[48:49], v[148:149] op_sel_hi:[1,0] neg_lo:[0,1] neg_hi:[0,1]
	v_pk_add_f32 v[66:67], v[66:67], v[148:149] op_sel_hi:[1,0] neg_lo:[0,1] neg_hi:[0,1]
	v_pk_add_f32 v[50:51], v[50:51], v[148:149] op_sel_hi:[1,0] neg_lo:[0,1] neg_hi:[0,1]
	v_pk_add_f32 v[68:69], v[68:69], v[148:149] op_sel_hi:[1,0] neg_lo:[0,1] neg_hi:[0,1]
	v_pk_add_f32 v[52:53], v[52:53], v[148:149] op_sel_hi:[1,0] neg_lo:[0,1] neg_hi:[0,1]
	v_pk_add_f32 v[70:71], v[70:71], v[148:149] op_sel_hi:[1,0] neg_lo:[0,1] neg_hi:[0,1]
	v_pk_add_f32 v[54:55], v[54:55], v[148:149] op_sel_hi:[1,0] neg_lo:[0,1] neg_hi:[0,1]
	v_pk_add_f32 v[72:73], v[72:73], v[148:149] op_sel_hi:[1,0] neg_lo:[0,1] neg_hi:[0,1]
	v_pk_add_f32 v[56:57], v[56:57], v[148:149] op_sel_hi:[1,0] neg_lo:[0,1] neg_hi:[0,1]
	v_pk_add_f32 v[74:75], v[74:75], v[148:149] op_sel_hi:[1,0] neg_lo:[0,1] neg_hi:[0,1]
	v_pk_add_f32 v[58:59], v[58:59], v[148:149] op_sel_hi:[1,0] neg_lo:[0,1] neg_hi:[0,1]
	v_pk_add_f32 v[76:77], v[76:77], v[148:149] op_sel_hi:[1,0] neg_lo:[0,1] neg_hi:[0,1]
	v_pk_add_f32 v[60:61], v[60:61], v[148:149] op_sel_hi:[1,0] neg_lo:[0,1] neg_hi:[0,1]
	v_pk_add_f32 v[78:79], v[78:79], v[148:149] op_sel_hi:[1,0] neg_lo:[0,1] neg_hi:[0,1]
	v_pk_add_f32 v[62:63], v[62:63], v[148:149] op_sel_hi:[1,0] neg_lo:[0,1] neg_hi:[0,1]
	v_pk_mul_f32 v[30:31], v[30:31], v[160:161] op_sel_hi:[1,0]
	v_pk_mul_f32 v[28:29], v[28:29], v[160:161] op_sel_hi:[1,0]
	v_pk_mul_f32 v[26:27], v[26:27], v[160:161] op_sel_hi:[1,0]
	v_pk_mul_f32 v[24:25], v[24:25], v[160:161] op_sel_hi:[1,0]
	v_pk_mul_f32 v[22:23], v[22:23], v[160:161] op_sel_hi:[1,0]
	v_pk_mul_f32 v[20:21], v[20:21], v[160:161] op_sel_hi:[1,0]
	v_pk_mul_f32 v[18:19], v[18:19], v[160:161] op_sel_hi:[1,0]
	v_pk_mul_f32 v[16:17], v[16:17], v[160:161] op_sel_hi:[1,0]
	v_pk_mul_f32 v[14:15], v[14:15], v[160:161] op_sel_hi:[1,0]
	v_pk_mul_f32 v[12:13], v[12:13], v[160:161] op_sel_hi:[1,0]
	v_pk_mul_f32 v[10:11], v[10:11], v[160:161] op_sel_hi:[1,0]
	v_pk_mul_f32 v[8:9], v[8:9], v[160:161] op_sel_hi:[1,0]
	v_pk_mul_f32 v[6:7], v[6:7], v[160:161] op_sel_hi:[1,0]
	v_pk_mul_f32 v[4:5], v[4:5], v[160:161] op_sel_hi:[1,0]
	v_pk_mul_f32 v[2:3], v[2:3], v[160:161] op_sel_hi:[1,0]
	v_pk_mul_f32 v[0:1], v[0:1], v[160:161] op_sel_hi:[1,0]
	v_pk_mul_f32 v[152:153], v[152:153], v[160:161] op_sel_hi:[1,0]
	v_pk_mul_f32 v[150:151], v[150:151], v[160:161] op_sel_hi:[1,0]
.Lmla_norescale_2:
	v_exp_f32_e32 v160, v64
	v_exp_f32_e32 v161, v65
	v_exp_f32_e32 v64, v66
	v_exp_f32_e32 v65, v67
	v_exp_f32_e32 v68, v68
	v_exp_f32_e32 v69, v69
	v_exp_f32_e32 v66, v70
	v_exp_f32_e32 v67, v71
	v_cvt_pk_bf16_f32 v176, v160, v161
	v_cvt_pk_bf16_f32 v177, v64, v65
	v_cvt_pk_bf16_f32 v178, v68, v69
	v_cvt_pk_bf16_f32 v179, v66, v67
	v_exp_f32_e32 v70, v74
	v_exp_f32_e32 v71, v75
	s_waitcnt lgkmcnt(0)
	v_mfma_f32_32x32x16_bf16 v[16:31], v[136:139], v[176:179], v[16:31]
	v_exp_f32_e32 v136, v72
	v_exp_f32_e32 v137, v73
	v_exp_f32_e32 v74, v76
	v_exp_f32_e32 v75, v77
	v_exp_f32_e32 v72, v78
	v_exp_f32_e32 v73, v79
	v_exp_f32_e32 v76, v48
	v_mfma_f32_32x32x16_bf16 v[0:15], v[144:147], v[176:179], v[0:15]
	v_cvt_pk_bf16_f32 v144, v136, v137
	v_cvt_pk_bf16_f32 v145, v70, v71
	v_cvt_pk_bf16_f32 v146, v74, v75
	v_cvt_pk_bf16_f32 v147, v72, v73
	v_exp_f32_e32 v77, v49
	v_exp_f32_e32 v48, v50
	v_exp_f32_e32 v49, v51
	v_mfma_f32_32x32x16_bf16 v[16:31], v[124:127], v[144:147], v[16:31]
	v_exp_f32_e32 v52, v52
	v_exp_f32_e32 v53, v53
	v_exp_f32_e32 v50, v54
	v_exp_f32_e32 v51, v55
	v_cvt_pk_bf16_f32 v124, v76, v77
	v_cvt_pk_bf16_f32 v125, v48, v49
	v_cvt_pk_bf16_f32 v126, v52, v53
	v_mfma_f32_32x32x16_bf16 v[0:15], v[140:143], v[144:147], v[0:15]
	v_cvt_pk_bf16_f32 v127, v50, v51
	v_exp_f32_e32 v78, v56
	v_exp_f32_e32 v79, v57
	v_exp_f32_e32 v54, v58
	v_exp_f32_e32 v55, v59
	v_exp_f32_e32 v58, v60
	v_exp_f32_e32 v59, v61
	v_mfma_f32_32x32x16_bf16 v[16:31], v[132:135], v[124:127], v[16:31]
	v_exp_f32_e32 v56, v62
	v_exp_f32_e32 v57, v63
	v_cvt_pk_bf16_f32 v60, v78, v79
	v_cvt_pk_bf16_f32 v61, v54, v55
	v_cvt_pk_bf16_f32 v62, v58, v59
	v_cvt_pk_bf16_f32 v63, v56, v57
	v_mfma_f32_32x32x16_bf16 v[0:15], v[128:131], v[124:127], v[0:15]
	v_mfma_f32_32x32x16_bf16 v[16:31], v[120:123], v[60:63], v[16:31]
	v_mfma_f32_32x32x16_bf16 v[0:15], v[116:119], v[60:63], v[0:15]
	s_waitcnt vmcnt(1)
	ds_write_b128 v244, v[104:107] offset:13312
	s_mov_b64 exec, s[8:9]
	ds_write_b128 v245, v[108:111] offset:13312
	s_mov_b64 exec, -1
	s_waitcnt vmcnt(0)
	ds_write2_b64 v243, v[112:113], v[114:115] offset1:2
	v_pk_add_f32 v[48:49], v[64:65], v[48:49]
	v_pk_add_f32 v[60:61], v[160:161], v[76:77]
	v_pk_add_f32 v[48:49], v[152:153], v[48:49]
	v_pk_add_f32 v[50:51], v[66:67], v[50:51]
	v_pk_add_f32 v[60:61], v[150:151], v[60:61]
	v_pk_add_f32 v[52:53], v[68:69], v[52:53]
	v_pk_add_f32 v[48:49], v[50:51], v[48:49]
	v_pk_add_f32 v[50:51], v[70:71], v[54:55]
	v_pk_add_f32 v[52:53], v[52:53], v[60:61]
	v_pk_add_f32 v[60:61], v[136:137], v[78:79]
	v_pk_add_f32 v[48:49], v[50:51], v[48:49]
	v_pk_add_f32 v[50:51], v[72:73], v[56:57]
	v_pk_add_f32 v[52:53], v[60:61], v[52:53]
	v_pk_add_f32 v[58:59], v[74:75], v[58:59]
	v_pk_add_f32 v[152:153], v[50:51], v[48:49]
	v_pk_add_f32 v[150:151], v[58:59], v[52:53]
	s_cmp_lg_u32 s43, 63
	s_waitcnt lgkmcnt(0)
	s_barrier
	s_cbranch_scc0 .Lmla_exit
	ds_read_b128 v[48:51], v169 offset:13312
	ds_read_b128 v[52:55], v169 offset:13344
	ds_read_b128 v[116:119], v169 offset:19968
	ds_read_b128 v[120:123], v169 offset:20000
	global_load_dwordx4 v[104:107], v154, s[98:99]
	s_mov_b64 exec, s[8:9]
	global_load_dwordx4 v[108:111], v156, s[98:99]
	s_mov_b64 exec, -1
	global_load_dwordx4 v[112:115], v158, s[100:101]
	s_add_u32 s98, s98, 0x18000
	s_addc_u32 s99, s99, 0
	s_add_u32 s100, s100, 0x80
	s_addc_u32 s101, s101, 0
	s_waitcnt lgkmcnt(3)
	v_mfma_f32_32x32x16_bf16 v[64:79], v[48:51], v[100:103], v[32:47]
	ds_read_b128 v[124:127], v169 offset:13376
	ds_read_b128 v[128:131], v169 offset:13408
	ds_read_b128 v[132:135], v169 offset:20032
	ds_read_b128 v[136:139], v169 offset:20064
	s_waitcnt lgkmcnt(4)
	v_mfma_f32_32x32x16_bf16 v[64:79], v[52:55], v[96:99], v[64:79]
	v_mfma_f32_32x32x16_bf16 v[48:63], v[116:119], v[100:103], v[32:47]
	v_mfma_f32_32x32x16_bf16 v[48:63], v[120:123], v[96:99], v[48:63]
	s_waitcnt lgkmcnt(1)
	v_mfma_f32_32x32x16_bf16 v[64:79], v[124:127], v[92:95], v[64:79]
	v_mfma_f32_32x32x16_bf16 v[48:63], v[132:135], v[92:95], v[48:63]
	v_mfma_f32_32x32x16_bf16 v[64:79], v[128:131], v[88:91], v[64:79]
	ds_read_b128 v[116:119], v169 offset:13440
	ds_read_b128 v[120:123], v169 offset:13472
	ds_read_b128 v[128:131], v169 offset:20096
	ds_read_b128 v[176:179], v169 offset:20128
	s_waitcnt lgkmcnt(3)
	v_mfma_f32_32x32x16_bf16 v[48:63], v[136:139], v[88:91], v[48:63]
	v_mfma_f32_32x32x16_bf16 v[64:79], v[116:119], v[84:87], v[64:79]
	ds_read_b128 v[136:139], v170 offset:26624
	ds_read_b128 v[124:127], v170 offset:26656
	s_waitcnt lgkmcnt(3)
	v_mfma_f32_32x32x16_bf16 v[48:63], v[128:131], v[84:87], v[48:63]
	v_mfma_f32_32x32x16_bf16 v[64:79], v[120:123], v[80:83], v[64:79]
	ds_read_b128 v[132:135], v170 offset:26688
	ds_read_b128 v[120:123], v170 offset:26720
	ds_read_b128 v[144:147], v170 offset:31232
	ds_read_b128 v[140:143], v170 offset:31264
	ds_read_b128 v[128:131], v170 offset:31296
	ds_read_b128 v[116:119], v170 offset:31328
	s_waitcnt lgkmcnt(8)
	v_mfma_f32_32x32x16_bf16 v[48:63], v[176:179], v[80:83], v[48:63]
	s_add_i32 s43, s43, 1
	s_nop 3
	v_max3_f32 v148, v64, v65, v66
	v_max3_f32 v160, v67, v68, v69
	v_max3_f32 v148, v148, v70, v71
	v_max3_f32 v160, v160, v72, v73
	v_max3_f32 v148, v148, v74, v75
	v_max3_f32 v160, v160, v76, v77
	v_max3_f32 v148, v148, v78, v79
	v_max3_f32 v161, v48, v49, v50
	v_max3_f32 v176, v51, v52, v53
	v_max3_f32 v161, v161, v54, v55
	v_max3_f32 v176, v176, v56, v57
	v_max3_f32 v161, v161, v58, v59
	v_max3_f32 v176, v176, v60, v61
	v_max3_f32 v161, v161, v62, v63
	v_max3_f32 v148, v148, v160, v161
	v_max_f32_e32 v148, v148, v176
	v_cmp_lt_f32_e32 vcc, s59, v148
	s_cbranch_vccz .Lmla_norescale_3
	v_mov_b32_e32 v160, v148
	s_nop 1
	v_permlane32_swap_b32_e32 v148, v160
	v_max_f32_e32 v148, v148, v160
	v_max_f32_e32 v32, v148, v148
	v_max_f32_e32 v148, 0, v32
	v_exp_f32_e64 v160, -v148
	v_add_f32_e32 v168, v168, v148
	v_xor_b32_e32 v32, 0x80000000, v168
	v_mov_b32_e32 v33, v32
	v_mov_b32_e32 v34, v32
	v_mov_b32_e32 v35, v32
	v_mov_b32_e32 v36, v32
	v_mov_b32_e32 v37, v32
	v_mov_b32_e32 v38, v32
	v_mov_b32_e32 v39, v32
	v_mov_b32_e32 v40, v32
	v_mov_b32_e32 v41, v32
	v_mov_b32_e32 v42, v32
	v_mov_b32_e32 v43, v32
	v_mov_b32_e32 v44, v32
	v_mov_b32_e32 v45, v32
	v_mov_b32_e32 v46, v32
	v_mov_b32_e32 v47, v32
	v_pk_add_f32 v[64:65], v[64:65], v[148:149] op_sel_hi:[1,0] neg_lo:[0,1] neg_hi:[0,1]
	v_pk_add_f32 v[48:49], v[48:49], v[148:149] op_sel_hi:[1,0] neg_lo:[0,1] neg_hi:[0,1]
	v_pk_add_f32 v[66:67], v[66:67], v[148:149] op_sel_hi:[1,0] neg_lo:[0,1] neg_hi:[0,1]
	v_pk_add_f32 v[50:51], v[50:51], v[148:149] op_sel_hi:[1,0] neg_lo:[0,1] neg_hi:[0,1]
	v_pk_add_f32 v[68:69], v[68:69], v[148:149] op_sel_hi:[1,0] neg_lo:[0,1] neg_hi:[0,1]
	v_pk_add_f32 v[52:53], v[52:53], v[148:149] op_sel_hi:[1,0] neg_lo:[0,1] neg_hi:[0,1]
	v_pk_add_f32 v[70:71], v[70:71], v[148:149] op_sel_hi:[1,0] neg_lo:[0,1] neg_hi:[0,1]
	v_pk_add_f32 v[54:55], v[54:55], v[148:149] op_sel_hi:[1,0] neg_lo:[0,1] neg_hi:[0,1]
	v_pk_add_f32 v[72:73], v[72:73], v[148:149] op_sel_hi:[1,0] neg_lo:[0,1] neg_hi:[0,1]
	v_pk_add_f32 v[56:57], v[56:57], v[148:149] op_sel_hi:[1,0] neg_lo:[0,1] neg_hi:[0,1]
	v_pk_add_f32 v[74:75], v[74:75], v[148:149] op_sel_hi:[1,0] neg_lo:[0,1] neg_hi:[0,1]
	v_pk_add_f32 v[58:59], v[58:59], v[148:149] op_sel_hi:[1,0] neg_lo:[0,1] neg_hi:[0,1]
	v_pk_add_f32 v[76:77], v[76:77], v[148:149] op_sel_hi:[1,0] neg_lo:[0,1] neg_hi:[0,1]
	v_pk_add_f32 v[60:61], v[60:61], v[148:149] op_sel_hi:[1,0] neg_lo:[0,1] neg_hi:[0,1]
	v_pk_add_f32 v[78:79], v[78:79], v[148:149] op_sel_hi:[1,0] neg_lo:[0,1] neg_hi:[0,1]
	v_pk_add_f32 v[62:63], v[62:63], v[148:149] op_sel_hi:[1,0] neg_lo:[0,1] neg_hi:[0,1]
	v_pk_mul_f32 v[30:31], v[30:31], v[160:161] op_sel_hi:[1,0]
	v_pk_mul_f32 v[28:29], v[28:29], v[160:161] op_sel_hi:[1,0]
	v_pk_mul_f32 v[26:27], v[26:27], v[160:161] op_sel_hi:[1,0]
	v_pk_mul_f32 v[24:25], v[24:25], v[160:161] op_sel_hi:[1,0]
	v_pk_mul_f32 v[22:23], v[22:23], v[160:161] op_sel_hi:[1,0]
	v_pk_mul_f32 v[20:21], v[20:21], v[160:161] op_sel_hi:[1,0]
	v_pk_mul_f32 v[18:19], v[18:19], v[160:161] op_sel_hi:[1,0]
	v_pk_mul_f32 v[16:17], v[16:17], v[160:161] op_sel_hi:[1,0]
	v_pk_mul_f32 v[14:15], v[14:15], v[160:161] op_sel_hi:[1,0]
	v_pk_mul_f32 v[12:13], v[12:13], v[160:161] op_sel_hi:[1,0]
	v_pk_mul_f32 v[10:11], v[10:11], v[160:161] op_sel_hi:[1,0]
	v_pk_mul_f32 v[8:9], v[8:9], v[160:161] op_sel_hi:[1,0]
	v_pk_mul_f32 v[6:7], v[6:7], v[160:161] op_sel_hi:[1,0]
	v_pk_mul_f32 v[4:5], v[4:5], v[160:161] op_sel_hi:[1,0]
	v_pk_mul_f32 v[2:3], v[2:3], v[160:161] op_sel_hi:[1,0]
	v_pk_mul_f32 v[0:1], v[0:1], v[160:161] op_sel_hi:[1,0]
	v_pk_mul_f32 v[152:153], v[152:153], v[160:161] op_sel_hi:[1,0]
	v_pk_mul_f32 v[150:151], v[150:151], v[160:161] op_sel_hi:[1,0]
; #define AT_QK_LD0(kb_) do { if constexpr (NEGM) { const LAS unsigned char* kbp_ = Kl + (kb_) * KBUF + r32 * KROWB + hi * 16; AT_KLD2(0); __builtin_amdgcn_sched_barrier(0); } } while (0)
; template <int DQK, int DV, int RH, bool NEGM> ...
;     ...
;     const int NT = nkv / 64;
;     AT_GLOAD(0); AT_LSTORE(0, 0); __syncthreads();
;     int vs_prev = 2, vs_cur = 0, vs_next = 1;
;     if (!grpB) {
;         for (int t = 0; t < NT; ++t) {
;             const int kb = t & 1;
;             if (t + 1 < NT) AT_GLOAD(t + 1);
;             f32x16 p[RH][2];
;             AT_QK_LD0(kb); AT_QK(kb); AT_VLOAD(vs_cur); AT_SOFTMAX(); AT_PV(vs_cur);
;             if (t + 1 < NT) AT_LSTORE(kb ^ 1, vs_next);
;             __syncthreads();
.Lmla_norescale_3:
	v_exp_f32_e32 v160, v64
	v_exp_f32_e32 v161, v65
	v_exp_f32_e32 v64, v66
	v_exp_f32_e32 v65, v67
	v_exp_f32_e32 v68, v68
	v_exp_f32_e32 v69, v69
	v_exp_f32_e32 v66, v70
	v_exp_f32_e32 v67, v71
	v_cvt_pk_bf16_f32 v176, v160, v161
	v_cvt_pk_bf16_f32 v177, v64, v65
	v_cvt_pk_bf16_f32 v178, v68, v69
	v_cvt_pk_bf16_f32 v179, v66, v67
	v_exp_f32_e32 v70, v74
	v_exp_f32_e32 v71, v75
	s_waitcnt lgkmcnt(0)
	v_mfma_f32_32x32x16_bf16 v[16:31], v[136:139], v[176:179], v[16:31]
	v_exp_f32_e32 v136, v72
	v_exp_f32_e32 v137, v73
	v_exp_f32_e32 v74, v76
	v_exp_f32_e32 v75, v77
	v_exp_f32_e32 v72, v78
	v_exp_f32_e32 v73, v79
	v_exp_f32_e32 v76, v48
	v_mfma_f32_32x32x16_bf16 v[0:15], v[144:147], v[176:179], v[0:15]
	v_cvt_pk_bf16_f32 v144, v136, v137
	v_cvt_pk_bf16_f32 v145, v70, v71
	v_cvt_pk_bf16_f32 v146, v74, v75
	v_cvt_pk_bf16_f32 v147, v72, v73
	v_exp_f32_e32 v77, v49
	v_exp_f32_e32 v48, v50
	v_exp_f32_e32 v49, v51
	v_mfma_f32_32x32x16_bf16 v[16:31], v[124:127], v[144:147], v[16:31]
	v_exp_f32_e32 v52, v52
	v_exp_f32_e32 v53, v53
	v_exp_f32_e32 v50, v54
	v_exp_f32_e32 v51, v55
	v_cvt_pk_bf16_f32 v124, v76, v77
	v_cvt_pk_bf16_f32 v125, v48, v49
	v_cvt_pk_bf16_f32 v126, v52, v53
	v_mfma_f32_32x32x16_bf16 v[0:15], v[140:143], v[144:147], v[0:15]
	v_cvt_pk_bf16_f32 v127, v50, v51
	v_exp_f32_e32 v78, v56
	v_exp_f32_e32 v79, v57
	v_exp_f32_e32 v54, v58
	v_exp_f32_e32 v55, v59
	v_exp_f32_e32 v58, v60
	v_exp_f32_e32 v59, v61
	v_mfma_f32_32x32x16_bf16 v[16:31], v[132:135], v[124:127], v[16:31]
	v_exp_f32_e32 v56, v62
	v_exp_f32_e32 v57, v63
	v_cvt_pk_bf16_f32 v60, v78, v79
	v_cvt_pk_bf16_f32 v61, v54, v55
	v_cvt_pk_bf16_f32 v62, v58, v59
	v_cvt_pk_bf16_f32 v63, v56, v57
	v_mfma_f32_32x32x16_bf16 v[0:15], v[128:131], v[124:127], v[0:15]
	v_mfma_f32_32x32x16_bf16 v[16:31], v[120:123], v[60:63], v[16:31]
	v_mfma_f32_32x32x16_bf16 v[0:15], v[116:119], v[60:63], v[0:15]
	s_waitcnt vmcnt(1)
	ds_write_b128 v244, v[104:107]
	s_mov_b64 exec, s[8:9]
	ds_write_b128 v245, v[108:111]
	s_mov_b64 exec, -1
	s_waitcnt vmcnt(0)
	ds_write2_b64 v246, v[112:113], v[114:115] offset1:2
	v_pk_add_f32 v[48:49], v[64:65], v[48:49]
	v_pk_add_f32 v[60:61], v[160:161], v[76:77]
	v_pk_add_f32 v[48:49], v[152:153], v[48:49]
	v_pk_add_f32 v[50:51], v[66:67], v[50:51]
	v_pk_add_f32 v[60:61], v[150:151], v[60:61]
	v_pk_add_f32 v[52:53], v[68:69], v[52:53]
	v_pk_add_f32 v[48:49], v[50:51], v[48:49]
	v_pk_add_f32 v[50:51], v[70:71], v[54:55]
	v_pk_add_f32 v[52:53], v[52:53], v[60:61]
	v_pk_add_f32 v[60:61], v[136:137], v[78:79]
	v_pk_add_f32 v[48:49], v[50:51], v[48:49]
	v_pk_add_f32 v[50:51], v[72:73], v[56:57]
	v_pk_add_f32 v[52:53], v[60:61], v[52:53]
	v_pk_add_f32 v[58:59], v[74:75], v[58:59]
	v_pk_add_f32 v[152:153], v[50:51], v[48:49]
	v_pk_add_f32 v[150:151], v[58:59], v[52:53]
	s_waitcnt lgkmcnt(0)
	s_barrier
	ds_read_b128 v[48:51], v169
	ds_read_b128 v[52:55], v169 offset:32
	ds_read_b128 v[116:119], v169 offset:6656
	ds_read_b128 v[120:123], v169 offset:6688
	global_load_dwordx4 v[104:107], v154, s[98:99]
	s_mov_b64 exec, s[8:9]
	global_load_dwordx4 v[108:111], v156, s[98:99]
	s_mov_b64 exec, -1
	global_load_dwordx4 v[112:115], v158, s[100:101]
	s_add_u32 s98, s98, 0x18000
	s_addc_u32 s99, s99, 0
	s_add_u32 s100, s100, 0x80
	s_addc_u32 s101, s101, 0
	s_waitcnt lgkmcnt(3)
	v_mfma_f32_32x32x16_bf16 v[64:79], v[48:51], v[100:103], v[32:47]
	ds_read_b128 v[124:127], v169 offset:64
	ds_read_b128 v[128:131], v169 offset:96
	ds_read_b128 v[132:135], v169 offset:6720
	ds_read_b128 v[136:139], v169 offset:6752
	s_waitcnt lgkmcnt(4)
	v_mfma_f32_32x32x16_bf16 v[64:79], v[52:55], v[96:99], v[64:79]
	v_mfma_f32_32x32x16_bf16 v[48:63], v[116:119], v[100:103], v[32:47]
	v_mfma_f32_32x32x16_bf16 v[48:63], v[120:123], v[96:99], v[48:63]
	s_waitcnt lgkmcnt(1)
	v_mfma_f32_32x32x16_bf16 v[64:79], v[124:127], v[92:95], v[64:79]
	v_mfma_f32_32x32x16_bf16 v[48:63], v[132:135], v[92:95], v[48:63]
	v_mfma_f32_32x32x16_bf16 v[64:79], v[128:131], v[88:91], v[64:79]
	ds_read_b128 v[116:119], v169 offset:128
	ds_read_b128 v[120:123], v169 offset:160
	ds_read_b128 v[128:131], v169 offset:6784
	ds_read_b128 v[176:179], v169 offset:6816
	s_waitcnt lgkmcnt(3)
	v_mfma_f32_32x32x16_bf16 v[48:63], v[136:139], v[88:91], v[48:63]
	v_mfma_f32_32x32x16_bf16 v[64:79], v[116:119], v[84:87], v[64:79]
	ds_read_b128 v[136:139], v170 offset:35840
	ds_read_b128 v[124:127], v170 offset:35872
	s_waitcnt lgkmcnt(3)
	v_mfma_f32_32x32x16_bf16 v[48:63], v[128:131], v[84:87], v[48:63]
	v_mfma_f32_32x32x16_bf16 v[64:79], v[120:123], v[80:83], v[64:79]
	ds_read_b128 v[132:135], v170 offset:35904
	ds_read_b128 v[120:123], v170 offset:35936
	ds_read_b128 v[144:147], v170 offset:40448
	ds_read_b128 v[140:143], v170 offset:40480
	ds_read_b128 v[128:131], v170 offset:40512
	ds_read_b128 v[116:119], v170 offset:40544
	s_waitcnt lgkmcnt(8)
	v_mfma_f32_32x32x16_bf16 v[48:63], v[176:179], v[80:83], v[48:63]
	s_add_i32 s43, s43, 1
	s_nop 3
	v_max3_f32 v148, v64, v65, v66
	v_max3_f32 v160, v67, v68, v69
	v_max3_f32 v148, v148, v70, v71
	v_max3_f32 v160, v160, v72, v73
	v_max3_f32 v148, v148, v74, v75
	v_max3_f32 v160, v160, v76, v77
	v_max3_f32 v148, v148, v78, v79
	v_max3_f32 v161, v48, v49, v50
	v_max3_f32 v176, v51, v52, v53
	v_max3_f32 v161, v161, v54, v55
	v_max3_f32 v176, v176, v56, v57
	v_max3_f32 v161, v161, v58, v59
	v_max3_f32 v176, v176, v60, v61
	v_max3_f32 v161, v161, v62, v63
	v_max3_f32 v148, v148, v160, v161
	v_max_f32_e32 v148, v148, v176
	v_cmp_lt_f32_e32 vcc, s59, v148
	s_cbranch_vccz .Lmla_norescale_4
; #define AT_QK_LD0(kb_) do { if constexpr (NEGM) { const LAS unsigned char* kbp_ = Kl + (kb_) * KBUF + r32 * KROWB + hi * 16; AT_KLD2(0); __builtin_amdgcn_sched_barrier(0); } } while (0)
; template <int DQK, int DV, int RH, bool NEGM> ...
;     ...
;     const int NT = nkv / 64;
;     AT_GLOAD(0); AT_LSTORE(0, 0); __syncthreads();
;     int vs_prev = 2, vs_cur = 0, vs_next = 1;
;     if (!grpB) {
;         for (int t = 0; t < NT; ++t) {
;             const int kb = t & 1;
;             if (t + 1 < NT) AT_GLOAD(t + 1);
;             f32x16 p[RH][2];
;             AT_QK_LD0(kb); AT_QK(kb); AT_VLOAD(vs_cur); AT_SOFTMAX(); AT_PV(vs_cur);
;             if (t + 1 < NT) AT_LSTORE(kb ^ 1, vs_next);
;             __syncthreads();
	v_mov_b32_e32 v160, v148
	s_nop 1
	v_permlane32_swap_b32_e32 v148, v160
	v_max_f32_e32 v148, v148, v160
	v_max_f32_e32 v32, v148, v148
	v_max_f32_e32 v148, 0, v32
	v_exp_f32_e64 v160, -v148
	v_add_f32_e32 v168, v168, v148
	v_xor_b32_e32 v32, 0x80000000, v168
	v_mov_b32_e32 v33, v32
	v_mov_b32_e32 v34, v32
	v_mov_b32_e32 v35, v32
	v_mov_b32_e32 v36, v32
	v_mov_b32_e32 v37, v32
	v_mov_b32_e32 v38, v32
	v_mov_b32_e32 v39, v32
	v_mov_b32_e32 v40, v32
	v_mov_b32_e32 v41, v32
	v_mov_b32_e32 v42, v32
	v_mov_b32_e32 v43, v32
	v_mov_b32_e32 v44, v32
	v_mov_b32_e32 v45, v32
	v_mov_b32_e32 v46, v32
	v_mov_b32_e32 v47, v32
	v_pk_add_f32 v[64:65], v[64:65], v[148:149] op_sel_hi:[1,0] neg_lo:[0,1] neg_hi:[0,1]
	v_pk_add_f32 v[48:49], v[48:49], v[148:149] op_sel_hi:[1,0] neg_lo:[0,1] neg_hi:[0,1]
	v_pk_add_f32 v[66:67], v[66:67], v[148:149] op_sel_hi:[1,0] neg_lo:[0,1] neg_hi:[0,1]
	v_pk_add_f32 v[50:51], v[50:51], v[148:149] op_sel_hi:[1,0] neg_lo:[0,1] neg_hi:[0,1]
	v_pk_add_f32 v[68:69], v[68:69], v[148:149] op_sel_hi:[1,0] neg_lo:[0,1] neg_hi:[0,1]
	v_pk_add_f32 v[52:53], v[52:53], v[148:149] op_sel_hi:[1,0] neg_lo:[0,1] neg_hi:[0,1]
	v_pk_add_f32 v[70:71], v[70:71], v[148:149] op_sel_hi:[1,0] neg_lo:[0,1] neg_hi:[0,1]
	v_pk_add_f32 v[54:55], v[54:55], v[148:149] op_sel_hi:[1,0] neg_lo:[0,1] neg_hi:[0,1]
	v_pk_add_f32 v[72:73], v[72:73], v[148:149] op_sel_hi:[1,0] neg_lo:[0,1] neg_hi:[0,1]
	v_pk_add_f32 v[56:57], v[56:57], v[148:149] op_sel_hi:[1,0] neg_lo:[0,1] neg_hi:[0,1]
	v_pk_add_f32 v[74:75], v[74:75], v[148:149] op_sel_hi:[1,0] neg_lo:[0,1] neg_hi:[0,1]
	v_pk_add_f32 v[58:59], v[58:59], v[148:149] op_sel_hi:[1,0] neg_lo:[0,1] neg_hi:[0,1]
	v_pk_add_f32 v[76:77], v[76:77], v[148:149] op_sel_hi:[1,0] neg_lo:[0,1] neg_hi:[0,1]
	v_pk_add_f32 v[60:61], v[60:61], v[148:149] op_sel_hi:[1,0] neg_lo:[0,1] neg_hi:[0,1]
	v_pk_add_f32 v[78:79], v[78:79], v[148:149] op_sel_hi:[1,0] neg_lo:[0,1] neg_hi:[0,1]
	v_pk_add_f32 v[62:63], v[62:63], v[148:149] op_sel_hi:[1,0] neg_lo:[0,1] neg_hi:[0,1]
	v_pk_mul_f32 v[30:31], v[30:31], v[160:161] op_sel_hi:[1,0]
	v_pk_mul_f32 v[28:29], v[28:29], v[160:161] op_sel_hi:[1,0]
	v_pk_mul_f32 v[26:27], v[26:27], v[160:161] op_sel_hi:[1,0]
	v_pk_mul_f32 v[24:25], v[24:25], v[160:161] op_sel_hi:[1,0]
	v_pk_mul_f32 v[22:23], v[22:23], v[160:161] op_sel_hi:[1,0]
	v_pk_mul_f32 v[20:21], v[20:21], v[160:161] op_sel_hi:[1,0]
	v_pk_mul_f32 v[18:19], v[18:19], v[160:161] op_sel_hi:[1,0]
	v_pk_mul_f32 v[16:17], v[16:17], v[160:161] op_sel_hi:[1,0]
	v_pk_mul_f32 v[14:15], v[14:15], v[160:161] op_sel_hi:[1,0]
	v_pk_mul_f32 v[12:13], v[12:13], v[160:161] op_sel_hi:[1,0]
	v_pk_mul_f32 v[10:11], v[10:11], v[160:161] op_sel_hi:[1,0]
	v_pk_mul_f32 v[8:9], v[8:9], v[160:161] op_sel_hi:[1,0]
	v_pk_mul_f32 v[6:7], v[6:7], v[160:161] op_sel_hi:[1,0]
	v_pk_mul_f32 v[4:5], v[4:5], v[160:161] op_sel_hi:[1,0]
	v_pk_mul_f32 v[2:3], v[2:3], v[160:161] op_sel_hi:[1,0]
	v_pk_mul_f32 v[0:1], v[0:1], v[160:161] op_sel_hi:[1,0]
	v_pk_mul_f32 v[152:153], v[152:153], v[160:161] op_sel_hi:[1,0]
	v_pk_mul_f32 v[150:151], v[150:151], v[160:161] op_sel_hi:[1,0]
.Lmla_norescale_4:
	v_exp_f32_e32 v160, v64
	v_exp_f32_e32 v161, v65
	v_exp_f32_e32 v64, v66
	v_exp_f32_e32 v65, v67
	v_exp_f32_e32 v68, v68
	v_exp_f32_e32 v69, v69
	v_exp_f32_e32 v66, v70
	v_exp_f32_e32 v67, v71
	v_cvt_pk_bf16_f32 v176, v160, v161
	v_cvt_pk_bf16_f32 v177, v64, v65
	v_cvt_pk_bf16_f32 v178, v68, v69
	v_cvt_pk_bf16_f32 v179, v66, v67
	v_exp_f32_e32 v70, v74
	v_exp_f32_e32 v71, v75
	s_waitcnt lgkmcnt(0)
	v_mfma_f32_32x32x16_bf16 v[16:31], v[136:139], v[176:179], v[16:31]
	v_exp_f32_e32 v136, v72
	v_exp_f32_e32 v137, v73
	v_exp_f32_e32 v74, v76
	v_exp_f32_e32 v75, v77
	v_exp_f32_e32 v72, v78
	v_exp_f32_e32 v73, v79
	v_exp_f32_e32 v76, v48
	v_mfma_f32_32x32x16_bf16 v[0:15], v[144:147], v[176:179], v[0:15]
	v_cvt_pk_bf16_f32 v144, v136, v137
	v_cvt_pk_bf16_f32 v145, v70, v71
	v_cvt_pk_bf16_f32 v146, v74, v75
	v_cvt_pk_bf16_f32 v147, v72, v73
	v_exp_f32_e32 v77, v49
	v_exp_f32_e32 v48, v50
	v_exp_f32_e32 v49, v51
	v_mfma_f32_32x32x16_bf16 v[16:31], v[124:127], v[144:147], v[16:31]
	v_exp_f32_e32 v52, v52
	v_exp_f32_e32 v53, v53
	v_exp_f32_e32 v50, v54
	v_exp_f32_e32 v51, v55
	v_cvt_pk_bf16_f32 v124, v76, v77
	v_cvt_pk_bf16_f32 v125, v48, v49
	v_cvt_pk_bf16_f32 v126, v52, v53
	v_mfma_f32_32x32x16_bf16 v[0:15], v[140:143], v[144:147], v[0:15]
	v_cvt_pk_bf16_f32 v127, v50, v51
	v_exp_f32_e32 v78, v56
	v_exp_f32_e32 v79, v57
	v_exp_f32_e32 v54, v58
	v_exp_f32_e32 v55, v59
	v_exp_f32_e32 v58, v60
	v_exp_f32_e32 v59, v61
	v_mfma_f32_32x32x16_bf16 v[16:31], v[132:135], v[124:127], v[16:31]
	v_exp_f32_e32 v56, v62
	v_exp_f32_e32 v57, v63
	v_cvt_pk_bf16_f32 v60, v78, v79
	v_cvt_pk_bf16_f32 v61, v54, v55
	v_cvt_pk_bf16_f32 v62, v58, v59
	v_cvt_pk_bf16_f32 v63, v56, v57
	v_mfma_f32_32x32x16_bf16 v[0:15], v[128:131], v[124:127], v[0:15]
	v_mfma_f32_32x32x16_bf16 v[16:31], v[120:123], v[60:63], v[16:31]
	v_mfma_f32_32x32x16_bf16 v[0:15], v[116:119], v[60:63], v[0:15]
	s_waitcnt vmcnt(1)
	ds_write_b128 v244, v[104:107] offset:13312
	s_mov_b64 exec, s[8:9]
	ds_write_b128 v245, v[108:111] offset:13312
	s_mov_b64 exec, -1
	s_waitcnt vmcnt(0)
	ds_write2_b64 v247, v[112:113], v[114:115] offset1:2
	v_pk_add_f32 v[48:49], v[64:65], v[48:49]
	v_pk_add_f32 v[60:61], v[160:161], v[76:77]
	v_pk_add_f32 v[48:49], v[152:153], v[48:49]
	v_pk_add_f32 v[50:51], v[66:67], v[50:51]
	v_pk_add_f32 v[60:61], v[150:151], v[60:61]
	v_pk_add_f32 v[52:53], v[68:69], v[52:53]
	v_pk_add_f32 v[48:49], v[50:51], v[48:49]
	v_pk_add_f32 v[50:51], v[70:71], v[54:55]
	v_pk_add_f32 v[52:53], v[52:53], v[60:61]
	v_pk_add_f32 v[60:61], v[136:137], v[78:79]
	v_pk_add_f32 v[48:49], v[50:51], v[48:49]
	v_pk_add_f32 v[50:51], v[72:73], v[56:57]
	v_pk_add_f32 v[52:53], v[60:61], v[52:53]
	v_pk_add_f32 v[58:59], v[74:75], v[58:59]
	v_pk_add_f32 v[152:153], v[50:51], v[48:49]
	v_pk_add_f32 v[150:151], v[58:59], v[52:53]
	s_waitcnt lgkmcnt(0)
	s_barrier
	ds_read_b128 v[48:51], v169 offset:13312
	ds_read_b128 v[52:55], v169 offset:13344
	ds_read_b128 v[116:119], v169 offset:19968
	ds_read_b128 v[120:123], v169 offset:20000
	global_load_dwordx4 v[104:107], v154, s[98:99]
	s_mov_b64 exec, s[8:9]
	global_load_dwordx4 v[108:111], v156, s[98:99]
	s_mov_b64 exec, -1
	global_load_dwordx4 v[112:115], v158, s[100:101]
	s_add_u32 s98, s98, 0x18000
	s_addc_u32 s99, s99, 0
	s_add_u32 s100, s100, 0x80
	s_addc_u32 s101, s101, 0
	s_waitcnt lgkmcnt(3)
	v_mfma_f32_32x32x16_bf16 v[64:79], v[48:51], v[100:103], v[32:47]
	ds_read_b128 v[124:127], v169 offset:13376
	ds_read_b128 v[128:131], v169 offset:13408
	ds_read_b128 v[132:135], v169 offset:20032
	ds_read_b128 v[136:139], v169 offset:20064
	s_waitcnt lgkmcnt(4)
	v_mfma_f32_32x32x16_bf16 v[64:79], v[52:55], v[96:99], v[64:79]
	v_mfma_f32_32x32x16_bf16 v[48:63], v[116:119], v[100:103], v[32:47]
	v_mfma_f32_32x32x16_bf16 v[48:63], v[120:123], v[96:99], v[48:63]
	s_waitcnt lgkmcnt(1)
	v_mfma_f32_32x32x16_bf16 v[64:79], v[124:127], v[92:95], v[64:79]
	v_mfma_f32_32x32x16_bf16 v[48:63], v[132:135], v[92:95], v[48:63]
	v_mfma_f32_32x32x16_bf16 v[64:79], v[128:131], v[88:91], v[64:79]
	ds_read_b128 v[116:119], v169 offset:13440
	ds_read_b128 v[120:123], v169 offset:13472
	ds_read_b128 v[128:131], v169 offset:20096
	ds_read_b128 v[176:179], v169 offset:20128
	s_waitcnt lgkmcnt(3)
	v_mfma_f32_32x32x16_bf16 v[48:63], v[136:139], v[88:91], v[48:63]
	v_mfma_f32_32x32x16_bf16 v[64:79], v[116:119], v[84:87], v[64:79]
	ds_read_b128 v[136:139], v170 offset:45056
	ds_read_b128 v[124:127], v170 offset:45088
	s_waitcnt lgkmcnt(3)
	v_mfma_f32_32x32x16_bf16 v[48:63], v[128:131], v[84:87], v[48:63]
	v_mfma_f32_32x32x16_bf16 v[64:79], v[120:123], v[80:83], v[64:79]
	ds_read_b128 v[132:135], v170 offset:45120
	ds_read_b128 v[120:123], v170 offset:45152
	ds_read_b128 v[144:147], v170 offset:49664
	ds_read_b128 v[140:143], v170 offset:49696
	ds_read_b128 v[128:131], v170 offset:49728
	ds_read_b128 v[116:119], v170 offset:49760
	s_waitcnt lgkmcnt(8)
	v_mfma_f32_32x32x16_bf16 v[48:63], v[176:179], v[80:83], v[48:63]
	s_add_i32 s43, s43, 1
	s_nop 3
	v_max3_f32 v148, v64, v65, v66
	v_max3_f32 v160, v67, v68, v69
	v_max3_f32 v148, v148, v70, v71
	v_max3_f32 v160, v160, v72, v73
	v_max3_f32 v148, v148, v74, v75
	v_max3_f32 v160, v160, v76, v77
	v_max3_f32 v148, v148, v78, v79
	v_max3_f32 v161, v48, v49, v50
	v_max3_f32 v176, v51, v52, v53
	v_max3_f32 v161, v161, v54, v55
	v_max3_f32 v176, v176, v56, v57
	v_max3_f32 v161, v161, v58, v59
	v_max3_f32 v176, v176, v60, v61
	v_max3_f32 v161, v161, v62, v63
	v_max3_f32 v148, v148, v160, v161
	v_max_f32_e32 v148, v148, v176
	v_cmp_lt_f32_e32 vcc, s59, v148
	s_cbranch_vccz .Lmla_norescale_5
	v_mov_b32_e32 v160, v148
	s_nop 1
	v_permlane32_swap_b32_e32 v148, v160
	v_max_f32_e32 v148, v148, v160
	v_max_f32_e32 v32, v148, v148
	v_max_f32_e32 v148, 0, v32
	v_exp_f32_e64 v160, -v148
	v_add_f32_e32 v168, v168, v148
	v_xor_b32_e32 v32, 0x80000000, v168
	v_mov_b32_e32 v33, v32
	v_mov_b32_e32 v34, v32
	v_mov_b32_e32 v35, v32
	v_mov_b32_e32 v36, v32
	v_mov_b32_e32 v37, v32
	v_mov_b32_e32 v38, v32
	v_mov_b32_e32 v39, v32
	v_mov_b32_e32 v40, v32
	v_mov_b32_e32 v41, v32
	v_mov_b32_e32 v42, v32
	v_mov_b32_e32 v43, v32
	v_mov_b32_e32 v44, v32
	v_mov_b32_e32 v45, v32
	v_mov_b32_e32 v46, v32
	v_mov_b32_e32 v47, v32
	v_pk_add_f32 v[64:65], v[64:65], v[148:149] op_sel_hi:[1,0] neg_lo:[0,1] neg_hi:[0,1]
	v_pk_add_f32 v[48:49], v[48:49], v[148:149] op_sel_hi:[1,0] neg_lo:[0,1] neg_hi:[0,1]
	v_pk_add_f32 v[66:67], v[66:67], v[148:149] op_sel_hi:[1,0] neg_lo:[0,1] neg_hi:[0,1]
	v_pk_add_f32 v[50:51], v[50:51], v[148:149] op_sel_hi:[1,0] neg_lo:[0,1] neg_hi:[0,1]
	v_pk_add_f32 v[68:69], v[68:69], v[148:149] op_sel_hi:[1,0] neg_lo:[0,1] neg_hi:[0,1]
	v_pk_add_f32 v[52:53], v[52:53], v[148:149] op_sel_hi:[1,0] neg_lo:[0,1] neg_hi:[0,1]
	v_pk_add_f32 v[70:71], v[70:71], v[148:149] op_sel_hi:[1,0] neg_lo:[0,1] neg_hi:[0,1]
	v_pk_add_f32 v[54:55], v[54:55], v[148:149] op_sel_hi:[1,0] neg_lo:[0,1] neg_hi:[0,1]
	v_pk_add_f32 v[72:73], v[72:73], v[148:149] op_sel_hi:[1,0] neg_lo:[0,1] neg_hi:[0,1]
	v_pk_add_f32 v[56:57], v[56:57], v[148:149] op_sel_hi:[1,0] neg_lo:[0,1] neg_hi:[0,1]
	v_pk_add_f32 v[74:75], v[74:75], v[148:149] op_sel_hi:[1,0] neg_lo:[0,1] neg_hi:[0,1]
	v_pk_add_f32 v[58:59], v[58:59], v[148:149] op_sel_hi:[1,0] neg_lo:[0,1] neg_hi:[0,1]
	v_pk_add_f32 v[76:77], v[76:77], v[148:149] op_sel_hi:[1,0] neg_lo:[0,1] neg_hi:[0,1]
	v_pk_add_f32 v[60:61], v[60:61], v[148:149] op_sel_hi:[1,0] neg_lo:[0,1] neg_hi:[0,1]
	v_pk_add_f32 v[78:79], v[78:79], v[148:149] op_sel_hi:[1,0] neg_lo:[0,1] neg_hi:[0,1]
	v_pk_add_f32 v[62:63], v[62:63], v[148:149] op_sel_hi:[1,0] neg_lo:[0,1] neg_hi:[0,1]
	v_pk_mul_f32 v[30:31], v[30:31], v[160:161] op_sel_hi:[1,0]
	v_pk_mul_f32 v[28:29], v[28:29], v[160:161] op_sel_hi:[1,0]
	v_pk_mul_f32 v[26:27], v[26:27], v[160:161] op_sel_hi:[1,0]
	v_pk_mul_f32 v[24:25], v[24:25], v[160:161] op_sel_hi:[1,0]
	v_pk_mul_f32 v[22:23], v[22:23], v[160:161] op_sel_hi:[1,0]
	v_pk_mul_f32 v[20:21], v[20:21], v[160:161] op_sel_hi:[1,0]
	v_pk_mul_f32 v[18:19], v[18:19], v[160:161] op_sel_hi:[1,0]
	v_pk_mul_f32 v[16:17], v[16:17], v[160:161] op_sel_hi:[1,0]
	v_pk_mul_f32 v[14:15], v[14:15], v[160:161] op_sel_hi:[1,0]
	v_pk_mul_f32 v[12:13], v[12:13], v[160:161] op_sel_hi:[1,0]
	v_pk_mul_f32 v[10:11], v[10:11], v[160:161] op_sel_hi:[1,0]
	v_pk_mul_f32 v[8:9], v[8:9], v[160:161] op_sel_hi:[1,0]
	v_pk_mul_f32 v[6:7], v[6:7], v[160:161] op_sel_hi:[1,0]
	v_pk_mul_f32 v[4:5], v[4:5], v[160:161] op_sel_hi:[1,0]
	v_pk_mul_f32 v[2:3], v[2:3], v[160:161] op_sel_hi:[1,0]
	v_pk_mul_f32 v[0:1], v[0:1], v[160:161] op_sel_hi:[1,0]
	v_pk_mul_f32 v[152:153], v[152:153], v[160:161] op_sel_hi:[1,0]
	v_pk_mul_f32 v[150:151], v[150:151], v[160:161] op_sel_hi:[1,0]
; #define AT_QK_LD0(kb_) do { if constexpr (NEGM) { const LAS unsigned char* kbp_ = Kl + (kb_) * KBUF + r32 * KROWB + hi * 16; AT_KLD2(0); __builtin_amdgcn_sched_barrier(0); } } while (0)
; template <int DQK, int DV, int RH, bool NEGM> ...
;     ...
;     const int NT = nkv / 64;
;     AT_GLOAD(0); AT_LSTORE(0, 0); __syncthreads();
;     int vs_prev = 2, vs_cur = 0, vs_next = 1;
;     if (!grpB) {
;         for (int t = 0; t < NT; ++t) {
;             const int kb = t & 1;
;             if (t + 1 < NT) AT_GLOAD(t + 1);
;             f32x16 p[RH][2];
;             AT_QK_LD0(kb); AT_QK(kb); AT_VLOAD(vs_cur); AT_SOFTMAX(); AT_PV(vs_cur);
;             if (t + 1 < NT) AT_LSTORE(kb ^ 1, vs_next);
;             __syncthreads();
.Lmla_norescale_5:
	v_exp_f32_e32 v160, v64
	v_exp_f32_e32 v161, v65
	v_exp_f32_e32 v64, v66
	v_exp_f32_e32 v65, v67
	v_exp_f32_e32 v68, v68
	v_exp_f32_e32 v69, v69
	v_exp_f32_e32 v66, v70
	v_exp_f32_e32 v67, v71
	v_cvt_pk_bf16_f32 v176, v160, v161
	v_cvt_pk_bf16_f32 v177, v64, v65
	v_cvt_pk_bf16_f32 v178, v68, v69
	v_cvt_pk_bf16_f32 v179, v66, v67
	v_exp_f32_e32 v70, v74
	v_exp_f32_e32 v71, v75
	s_waitcnt lgkmcnt(0)
	v_mfma_f32_32x32x16_bf16 v[16:31], v[136:139], v[176:179], v[16:31]
	v_exp_f32_e32 v136, v72
	v_exp_f32_e32 v137, v73
	v_exp_f32_e32 v74, v76
	v_exp_f32_e32 v75, v77
	v_exp_f32_e32 v72, v78
	v_exp_f32_e32 v73, v79
	v_exp_f32_e32 v76, v48
	v_mfma_f32_32x32x16_bf16 v[0:15], v[144:147], v[176:179], v[0:15]
	v_cvt_pk_bf16_f32 v144, v136, v137
	v_cvt_pk_bf16_f32 v145, v70, v71
	v_cvt_pk_bf16_f32 v146, v74, v75
	v_cvt_pk_bf16_f32 v147, v72, v73
	v_exp_f32_e32 v77, v49
	v_exp_f32_e32 v48, v50
	v_exp_f32_e32 v49, v51
	v_mfma_f32_32x32x16_bf16 v[16:31], v[124:127], v[144:147], v[16:31]
	v_exp_f32_e32 v52, v52
	v_exp_f32_e32 v53, v53
	v_exp_f32_e32 v50, v54
	v_exp_f32_e32 v51, v55
	v_cvt_pk_bf16_f32 v124, v76, v77
	v_cvt_pk_bf16_f32 v125, v48, v49
	v_cvt_pk_bf16_f32 v126, v52, v53
	v_mfma_f32_32x32x16_bf16 v[0:15], v[140:143], v[144:147], v[0:15]
	v_cvt_pk_bf16_f32 v127, v50, v51
	v_exp_f32_e32 v78, v56
	v_exp_f32_e32 v79, v57
	v_exp_f32_e32 v54, v58
	v_exp_f32_e32 v55, v59
	v_exp_f32_e32 v58, v60
	v_exp_f32_e32 v59, v61
	v_mfma_f32_32x32x16_bf16 v[16:31], v[132:135], v[124:127], v[16:31]
	v_exp_f32_e32 v56, v62
	v_exp_f32_e32 v57, v63
	v_cvt_pk_bf16_f32 v60, v78, v79
	v_cvt_pk_bf16_f32 v61, v54, v55
	v_cvt_pk_bf16_f32 v62, v58, v59
	v_cvt_pk_bf16_f32 v63, v56, v57
	v_mfma_f32_32x32x16_bf16 v[0:15], v[128:131], v[124:127], v[0:15]
	v_mfma_f32_32x32x16_bf16 v[16:31], v[120:123], v[60:63], v[16:31]
	v_mfma_f32_32x32x16_bf16 v[0:15], v[116:119], v[60:63], v[0:15]
	s_waitcnt vmcnt(1)
	ds_write_b128 v244, v[104:107]
	s_mov_b64 exec, s[8:9]
	ds_write_b128 v245, v[108:111]
	s_mov_b64 exec, -1
	s_waitcnt vmcnt(0)
	ds_write2_b64 v243, v[112:113], v[114:115] offset1:2
	v_pk_add_f32 v[48:49], v[64:65], v[48:49]
	v_pk_add_f32 v[60:61], v[160:161], v[76:77]
	v_pk_add_f32 v[48:49], v[152:153], v[48:49]
	v_pk_add_f32 v[50:51], v[66:67], v[50:51]
	v_pk_add_f32 v[60:61], v[150:151], v[60:61]
	v_pk_add_f32 v[52:53], v[68:69], v[52:53]
	v_pk_add_f32 v[48:49], v[50:51], v[48:49]
	v_pk_add_f32 v[50:51], v[70:71], v[54:55]
	v_pk_add_f32 v[52:53], v[52:53], v[60:61]
	v_pk_add_f32 v[60:61], v[136:137], v[78:79]
	v_pk_add_f32 v[48:49], v[50:51], v[48:49]
	v_pk_add_f32 v[50:51], v[72:73], v[56:57]
	v_pk_add_f32 v[52:53], v[60:61], v[52:53]
	v_pk_add_f32 v[58:59], v[74:75], v[58:59]
	v_pk_add_f32 v[152:153], v[50:51], v[48:49]
	v_pk_add_f32 v[150:151], v[58:59], v[52:53]
	s_waitcnt lgkmcnt(0)
	s_barrier
	ds_read_b128 v[48:51], v169
	ds_read_b128 v[52:55], v169 offset:32
	ds_read_b128 v[116:119], v169 offset:6656
	ds_read_b128 v[120:123], v169 offset:6688
	global_load_dwordx4 v[104:107], v154, s[98:99]
	s_mov_b64 exec, s[8:9]
	global_load_dwordx4 v[108:111], v156, s[98:99]
	s_mov_b64 exec, -1
	global_load_dwordx4 v[112:115], v158, s[100:101]
	s_add_u32 s98, s98, 0x18000
	s_addc_u32 s99, s99, 0
	s_add_u32 s100, s100, 0x80
	s_addc_u32 s101, s101, 0
	s_waitcnt lgkmcnt(3)
	v_mfma_f32_32x32x16_bf16 v[64:79], v[48:51], v[100:103], v[32:47]
	ds_read_b128 v[124:127], v169 offset:64
	ds_read_b128 v[128:131], v169 offset:96
	ds_read_b128 v[132:135], v169 offset:6720
	ds_read_b128 v[136:139], v169 offset:6752
	s_waitcnt lgkmcnt(4)
	v_mfma_f32_32x32x16_bf16 v[64:79], v[52:55], v[96:99], v[64:79]
	v_mfma_f32_32x32x16_bf16 v[48:63], v[116:119], v[100:103], v[32:47]
	v_mfma_f32_32x32x16_bf16 v[48:63], v[120:123], v[96:99], v[48:63]
	s_waitcnt lgkmcnt(1)
	v_mfma_f32_32x32x16_bf16 v[64:79], v[124:127], v[92:95], v[64:79]
	v_mfma_f32_32x32x16_bf16 v[48:63], v[132:135], v[92:95], v[48:63]
	v_mfma_f32_32x32x16_bf16 v[64:79], v[128:131], v[88:91], v[64:79]
	ds_read_b128 v[116:119], v169 offset:128
	ds_read_b128 v[120:123], v169 offset:160
	ds_read_b128 v[128:131], v169 offset:6784
	ds_read_b128 v[176:179], v169 offset:6816
	s_waitcnt lgkmcnt(3)
	v_mfma_f32_32x32x16_bf16 v[48:63], v[136:139], v[88:91], v[48:63]
	v_mfma_f32_32x32x16_bf16 v[64:79], v[116:119], v[84:87], v[64:79]
	ds_read_b128 v[136:139], v170 offset:26624
	ds_read_b128 v[124:127], v170 offset:26656
	s_waitcnt lgkmcnt(3)
	v_mfma_f32_32x32x16_bf16 v[48:63], v[128:131], v[84:87], v[48:63]
	v_mfma_f32_32x32x16_bf16 v[64:79], v[120:123], v[80:83], v[64:79]
	ds_read_b128 v[132:135], v170 offset:26688
	ds_read_b128 v[120:123], v170 offset:26720
	ds_read_b128 v[144:147], v170 offset:31232
	ds_read_b128 v[140:143], v170 offset:31264
	ds_read_b128 v[128:131], v170 offset:31296
	ds_read_b128 v[116:119], v170 offset:31328
	s_waitcnt lgkmcnt(8)
	v_mfma_f32_32x32x16_bf16 v[48:63], v[176:179], v[80:83], v[48:63]
	s_add_i32 s43, s43, 1
	s_nop 3
	v_max3_f32 v148, v64, v65, v66
	v_max3_f32 v160, v67, v68, v69
	v_max3_f32 v148, v148, v70, v71
	v_max3_f32 v160, v160, v72, v73
	v_max3_f32 v148, v148, v74, v75
	v_max3_f32 v160, v160, v76, v77
	v_max3_f32 v148, v148, v78, v79
	v_max3_f32 v161, v48, v49, v50
	v_max3_f32 v176, v51, v52, v53
	v_max3_f32 v161, v161, v54, v55
	v_max3_f32 v176, v176, v56, v57
	v_max3_f32 v161, v161, v58, v59
	v_max3_f32 v176, v176, v60, v61
	v_max3_f32 v161, v161, v62, v63
	v_max3_f32 v148, v148, v160, v161
	v_max_f32_e32 v148, v148, v176
	v_cmp_lt_f32_e32 vcc, s59, v148
	s_cbranch_vccz .Lmla_norescale_0
	v_mov_b32_e32 v160, v148
	s_nop 1
	v_permlane32_swap_b32_e32 v148, v160
	v_max_f32_e32 v148, v148, v160
	v_max_f32_e32 v32, v148, v148
	v_max_f32_e32 v148, 0, v32
	v_exp_f32_e64 v160, -v148
	v_add_f32_e32 v168, v168, v148
	v_xor_b32_e32 v32, 0x80000000, v168
	v_mov_b32_e32 v33, v32
	v_mov_b32_e32 v34, v32
	v_mov_b32_e32 v35, v32
	v_mov_b32_e32 v36, v32
	v_mov_b32_e32 v37, v32
	v_mov_b32_e32 v38, v32
	v_mov_b32_e32 v39, v32
	v_mov_b32_e32 v40, v32
	v_mov_b32_e32 v41, v32
	v_mov_b32_e32 v42, v32
	v_mov_b32_e32 v43, v32
	v_mov_b32_e32 v44, v32
	v_mov_b32_e32 v45, v32
	v_mov_b32_e32 v46, v32
	v_mov_b32_e32 v47, v32
	v_pk_add_f32 v[64:65], v[64:65], v[148:149] op_sel_hi:[1,0] neg_lo:[0,1] neg_hi:[0,1]
	v_pk_add_f32 v[48:49], v[48:49], v[148:149] op_sel_hi:[1,0] neg_lo:[0,1] neg_hi:[0,1]
	v_pk_add_f32 v[66:67], v[66:67], v[148:149] op_sel_hi:[1,0] neg_lo:[0,1] neg_hi:[0,1]
	v_pk_add_f32 v[50:51], v[50:51], v[148:149] op_sel_hi:[1,0] neg_lo:[0,1] neg_hi:[0,1]
	v_pk_add_f32 v[68:69], v[68:69], v[148:149] op_sel_hi:[1,0] neg_lo:[0,1] neg_hi:[0,1]
	v_pk_add_f32 v[52:53], v[52:53], v[148:149] op_sel_hi:[1,0] neg_lo:[0,1] neg_hi:[0,1]
	v_pk_add_f32 v[70:71], v[70:71], v[148:149] op_sel_hi:[1,0] neg_lo:[0,1] neg_hi:[0,1]
	v_pk_add_f32 v[54:55], v[54:55], v[148:149] op_sel_hi:[1,0] neg_lo:[0,1] neg_hi:[0,1]
	v_pk_add_f32 v[72:73], v[72:73], v[148:149] op_sel_hi:[1,0] neg_lo:[0,1] neg_hi:[0,1]
	v_pk_add_f32 v[56:57], v[56:57], v[148:149] op_sel_hi:[1,0] neg_lo:[0,1] neg_hi:[0,1]
	v_pk_add_f32 v[74:75], v[74:75], v[148:149] op_sel_hi:[1,0] neg_lo:[0,1] neg_hi:[0,1]
	v_pk_add_f32 v[58:59], v[58:59], v[148:149] op_sel_hi:[1,0] neg_lo:[0,1] neg_hi:[0,1]
	v_pk_add_f32 v[76:77], v[76:77], v[148:149] op_sel_hi:[1,0] neg_lo:[0,1] neg_hi:[0,1]
	v_pk_add_f32 v[60:61], v[60:61], v[148:149] op_sel_hi:[1,0] neg_lo:[0,1] neg_hi:[0,1]
	v_pk_add_f32 v[78:79], v[78:79], v[148:149] op_sel_hi:[1,0] neg_lo:[0,1] neg_hi:[0,1]
	v_pk_add_f32 v[62:63], v[62:63], v[148:149] op_sel_hi:[1,0] neg_lo:[0,1] neg_hi:[0,1]
	v_pk_mul_f32 v[30:31], v[30:31], v[160:161] op_sel_hi:[1,0]
	v_pk_mul_f32 v[28:29], v[28:29], v[160:161] op_sel_hi:[1,0]
	v_pk_mul_f32 v[26:27], v[26:27], v[160:161] op_sel_hi:[1,0]
	v_pk_mul_f32 v[24:25], v[24:25], v[160:161] op_sel_hi:[1,0]
	v_pk_mul_f32 v[22:23], v[22:23], v[160:161] op_sel_hi:[1,0]
	v_pk_mul_f32 v[20:21], v[20:21], v[160:161] op_sel_hi:[1,0]
	v_pk_mul_f32 v[18:19], v[18:19], v[160:161] op_sel_hi:[1,0]
	v_pk_mul_f32 v[16:17], v[16:17], v[160:161] op_sel_hi:[1,0]
	v_pk_mul_f32 v[14:15], v[14:15], v[160:161] op_sel_hi:[1,0]
	v_pk_mul_f32 v[12:13], v[12:13], v[160:161] op_sel_hi:[1,0]
	v_pk_mul_f32 v[10:11], v[10:11], v[160:161] op_sel_hi:[1,0]
	v_pk_mul_f32 v[8:9], v[8:9], v[160:161] op_sel_hi:[1,0]
	v_pk_mul_f32 v[6:7], v[6:7], v[160:161] op_sel_hi:[1,0]
	v_pk_mul_f32 v[4:5], v[4:5], v[160:161] op_sel_hi:[1,0]
	v_pk_mul_f32 v[2:3], v[2:3], v[160:161] op_sel_hi:[1,0]
	v_pk_mul_f32 v[0:1], v[0:1], v[160:161] op_sel_hi:[1,0]
	v_pk_mul_f32 v[152:153], v[152:153], v[160:161] op_sel_hi:[1,0]
	v_pk_mul_f32 v[150:151], v[150:151], v[160:161] op_sel_hi:[1,0]
